# phase-3 k_pe tiles: the 8-head replicated CK stores issued write-through (sc0 sc1) so the end-of-phase L2 writeback has less to flush
# speedup vs baseline: 1.0006x; 1.0006x over previous
.LBB0_1112:
	s_cmp_lt_i32 s40, 0
	s_cbranch_scc1 .LBB0_1111
	v_mov_b32_e32 v0, v161
	v_mov_b32_e32 v31, v186
	s_add_i32 s12, s41, 0xffffe000
	s_mov_b32 s13, s77
	s_lshl_b64 s[78:79], s[12:13], 11
	v_lshlrev_b32_e32 v1, 4, v31
	v_ashrrev_i32_e32 v32, 3, v31
	v_and_b32_e32 v30, 0x70, v1
	s_add_u32 vcc_lo, s39, s78
	v_readlane_b32 s13, v254, 36
	v_lshl_or_b32 v34, v32, 11, v30
	s_addc_u32 vcc_hi, s13, s79
	v_add_u32_e32 v35, 0x10000, v34
	v_add_u32_e32 v38, 0x20000, v34
	v_add_u32_e32 v39, 0x30000, v34
	s_barrier
	global_load_dwordx4 v[14:17], v34, vcc
	global_load_dwordx4 v[18:21], v35, vcc
	global_load_dwordx4 v[22:25], v38, vcc
	global_load_dwordx4 v[26:29], v39, vcc
	global_load_dwordx4 v[46:49], v34, s[10:11]
	global_load_dwordx4 v[50:53], v35, s[10:11]
	v_lshrrev_b32_e32 v33, 1, v31
	v_and_b32_e32 v31, 31, v31
	v_and_or_b32 v45, v33, 32, v31
	v_and_or_b32 v31, v33, s44, v31
	v_and_b32_e32 v78, 16, v33
	v_mad_u64_u32 v[32:33], s[78:79], v32, s43, v[30:31]
	v_mad_u64_u32 v[36:37], s[78:79], v31, s43, v[78:79]
	v_mad_u32_u24 v33, v45, s43, v78
	v_mov_b32_e32 v1, v0
	v_mov_b32_e32 v2, v0
	v_mov_b32_e32 v3, v0
	v_mov_b32_e32 v4, v0
	v_mov_b32_e32 v5, v0
	v_mov_b32_e32 v6, v0
	v_mov_b32_e32 v7, v0
	s_waitcnt vmcnt(6)
	v_mov_b32_e32 v8, v0
	v_mov_b32_e32 v9, v0
	v_mov_b32_e32 v10, v0
	v_mov_b32_e32 v11, v0
	v_mov_b32_e32 v12, v0
	v_mov_b32_e32 v13, v0
	s_waitcnt vmcnt(5)
	ds_write_b128 v32, v[14:17]
	s_waitcnt vmcnt(4)
	ds_write_b128 v32, v[18:21] offset:4608
	s_waitcnt vmcnt(3)
	ds_write_b128 v32, v[22:25] offset:9216
	s_waitcnt vmcnt(2)
	ds_write_b128 v32, v[26:29] offset:13824
	s_waitcnt vmcnt(1)
	ds_write_b128 v32, v[46:49] offset:36864
	s_waitcnt vmcnt(0)
	ds_write_b128 v32, v[50:53] offset:41472
	global_load_dwordx4 v[46:49], v34, vcc offset:128
	global_load_dwordx4 v[50:53], v35, vcc offset:128
	global_load_dwordx4 v[58:61], v38, vcc offset:128
	global_load_dwordx4 v[62:65], v39, vcc offset:128
	global_load_dwordx4 v[66:69], v34, s[18:19]
	global_load_dwordx4 v[70:73], v35, s[18:19]
	s_waitcnt lgkmcnt(0)
	s_barrier
	ds_read_b128 v[74:77], v36
	ds_read_b128 v[78:81], v36 offset:4608
	ds_read_b128 v[82:85], v36 offset:32
	ds_read_b128 v[86:89], v33 offset:36864
	v_mov_b32_e32 v14, v0
	v_mov_b32_e32 v15, v0
	ds_read_b128 v[90:93], v36 offset:4640
	ds_read_b128 v[94:97], v33 offset:36896
	s_waitcnt lgkmcnt(2)
	v_mfma_f32_32x32x16_bf16 v[16:31], v[74:77], v[86:89], v[0:15]
	v_mfma_f32_32x32x16_bf16 v[0:15], v[78:81], v[86:89], v[0:15]
	s_waitcnt lgkmcnt(0)
	v_mfma_f32_32x32x16_bf16 v[16:31], v[82:85], v[94:97], v[16:31]
	v_mfma_f32_32x32x16_bf16 v[0:15], v[90:93], v[94:97], v[0:15]
	ds_read_b128 v[74:77], v36 offset:64
	ds_read_b128 v[82:85], v36 offset:4672
	ds_read_b128 v[78:81], v33 offset:36928
	s_waitcnt lgkmcnt(0)
	v_mfma_f32_32x32x16_bf16 v[16:31], v[74:77], v[78:81], v[16:31]
	v_mfma_f32_32x32x16_bf16 v[0:15], v[82:85], v[78:81], v[0:15]
	global_load_dwordx4 v[74:77], v34, vcc offset:256
	global_load_dwordx4 v[78:81], v35, vcc offset:256
	global_load_dwordx4 v[82:85], v38, vcc offset:256
	global_load_dwordx4 v[86:89], v39, vcc offset:256
	global_load_dwordx4 v[90:93], v34, s[20:21]
	global_load_dwordx4 v[94:97], v35, s[20:21]
	s_waitcnt vmcnt(11)
	ds_write_b128 v32, v[46:49] offset:18432
	s_waitcnt vmcnt(10)
	ds_write_b128 v32, v[50:53] offset:23040
	s_waitcnt vmcnt(9)
	ds_write_b128 v32, v[58:61] offset:27648
	s_waitcnt vmcnt(8)
	ds_write_b128 v32, v[62:65] offset:32256
	ds_read_b128 v[46:49], v36 offset:96
	ds_read_b128 v[58:61], v36 offset:4704
	ds_read_b128 v[50:53], v33 offset:36960
	s_waitcnt vmcnt(7)
	ds_write_b128 v32, v[66:69] offset:46080
	s_waitcnt vmcnt(6)
	ds_write_b128 v32, v[70:73] offset:50688
	s_waitcnt lgkmcnt(2)
	v_mfma_f32_32x32x16_bf16 v[16:31], v[46:49], v[50:53], v[16:31]
	s_waitcnt lgkmcnt(0)
	s_barrier
	v_mfma_f32_32x32x16_bf16 v[0:15], v[58:61], v[50:53], v[0:15]
	ds_read_b128 v[46:49], v36 offset:18432
	ds_read_b128 v[58:61], v36 offset:23040
	ds_read_b128 v[50:53], v33 offset:46080
	ds_read_b128 v[62:65], v36 offset:18464
	ds_read_b128 v[66:69], v36 offset:23072
	ds_read_b128 v[70:73], v33 offset:46112
	s_waitcnt lgkmcnt(3)
	v_mfma_f32_32x32x16_bf16 v[16:31], v[46:49], v[50:53], v[16:31]
	v_mfma_f32_32x32x16_bf16 v[0:15], v[58:61], v[50:53], v[0:15]
	global_load_dwordx4 v[46:49], v34, vcc offset:384
	global_load_dwordx4 v[50:53], v35, vcc offset:384
	global_load_dwordx4 v[58:61], v38, vcc offset:384
	global_load_dwordx4 v[98:101], v39, vcc offset:384
	global_load_dwordx4 v[102:105], v34, s[22:23]
	global_load_dwordx4 v[106:109], v35, s[22:23]
	ds_read_b128 v[110:113], v36 offset:18496
	ds_read_b128 v[114:117], v36 offset:23104
	ds_read_b128 v[118:121], v33 offset:46144
	s_waitcnt vmcnt(11)
	ds_write_b128 v32, v[74:77]
	s_waitcnt vmcnt(10)
	ds_write_b128 v32, v[78:81] offset:4608
	s_waitcnt vmcnt(9)
	ds_write_b128 v32, v[82:85] offset:9216
	s_waitcnt vmcnt(8)
	ds_write_b128 v32, v[86:89] offset:13824
	s_waitcnt lgkmcnt(7)
	v_mfma_f32_32x32x16_bf16 v[16:31], v[62:65], v[70:73], v[16:31]
	v_mfma_f32_32x32x16_bf16 v[0:15], v[66:69], v[70:73], v[0:15]
	ds_read_b128 v[62:65], v36 offset:18528
	ds_read_b128 v[66:69], v36 offset:23136
	ds_read_b128 v[70:73], v33 offset:46176
	s_waitcnt vmcnt(7)
	ds_write_b128 v32, v[90:93] offset:36864
	s_waitcnt vmcnt(6)
	ds_write_b128 v32, v[94:97] offset:41472
	s_waitcnt lgkmcnt(0)
	s_barrier
	v_mfma_f32_32x32x16_bf16 v[16:31], v[110:113], v[118:121], v[16:31]
	v_mfma_f32_32x32x16_bf16 v[0:15], v[114:117], v[118:121], v[0:15]
	v_mfma_f32_32x32x16_bf16 v[16:31], v[62:65], v[70:73], v[16:31]
	v_mfma_f32_32x32x16_bf16 v[0:15], v[66:69], v[70:73], v[0:15]
	ds_read_b128 v[62:65], v36
	ds_read_b128 v[70:73], v36 offset:4608
	ds_read_b128 v[66:69], v33 offset:36864
	ds_read_b128 v[74:77], v36 offset:32
	ds_read_b128 v[78:81], v36 offset:4640
	ds_read_b128 v[82:85], v33 offset:36896
	s_waitcnt lgkmcnt(3)
	v_mfma_f32_32x32x16_bf16 v[16:31], v[62:65], v[66:69], v[16:31]
	v_mfma_f32_32x32x16_bf16 v[0:15], v[70:73], v[66:69], v[0:15]
	global_load_dwordx4 v[62:65], v34, vcc offset:512
	global_load_dwordx4 v[66:69], v35, vcc offset:512
	global_load_dwordx4 v[70:73], v38, vcc offset:512
	global_load_dwordx4 v[86:89], v39, vcc offset:512
	global_load_dwordx4 v[90:93], v34, s[24:25]
	global_load_dwordx4 v[94:97], v35, s[24:25]
	ds_read_b128 v[110:113], v36 offset:64
	ds_read_b128 v[114:117], v36 offset:4672
	ds_read_b128 v[118:121], v33 offset:36928
	s_waitcnt vmcnt(11)
	ds_write_b128 v32, v[46:49] offset:18432
	s_waitcnt vmcnt(10)
	ds_write_b128 v32, v[50:53] offset:23040
	s_waitcnt vmcnt(9)
	ds_write_b128 v32, v[58:61] offset:27648
	s_waitcnt vmcnt(8)
	ds_write_b128 v32, v[98:101] offset:32256
	s_waitcnt lgkmcnt(7)
	v_mfma_f32_32x32x16_bf16 v[16:31], v[74:77], v[82:85], v[16:31]
	v_mfma_f32_32x32x16_bf16 v[0:15], v[78:81], v[82:85], v[0:15]
	ds_read_b128 v[46:49], v36 offset:96
	ds_read_b128 v[50:53], v36 offset:4704
	ds_read_b128 v[58:61], v33 offset:36960
	s_waitcnt vmcnt(7)
	ds_write_b128 v32, v[102:105] offset:46080
	s_waitcnt vmcnt(6)
	ds_write_b128 v32, v[106:109] offset:50688
	s_waitcnt lgkmcnt(0)
	s_barrier
	v_mfma_f32_32x32x16_bf16 v[16:31], v[110:113], v[118:121], v[16:31]
	v_mfma_f32_32x32x16_bf16 v[0:15], v[114:117], v[118:121], v[0:15]
	v_mfma_f32_32x32x16_bf16 v[16:31], v[46:49], v[58:61], v[16:31]
	v_mfma_f32_32x32x16_bf16 v[0:15], v[50:53], v[58:61], v[0:15]
	ds_read_b128 v[46:49], v36 offset:18432
	ds_read_b128 v[58:61], v36 offset:23040
	ds_read_b128 v[50:53], v33 offset:46080
	ds_read_b128 v[74:77], v36 offset:18464
	ds_read_b128 v[78:81], v36 offset:23072
	ds_read_b128 v[82:85], v33 offset:46112
	s_waitcnt lgkmcnt(3)
	v_mfma_f32_32x32x16_bf16 v[16:31], v[46:49], v[50:53], v[16:31]
	v_mfma_f32_32x32x16_bf16 v[0:15], v[58:61], v[50:53], v[0:15]
	global_load_dwordx4 v[46:49], v34, vcc offset:640
	global_load_dwordx4 v[50:53], v35, vcc offset:640
	global_load_dwordx4 v[58:61], v38, vcc offset:640
	global_load_dwordx4 v[98:101], v39, vcc offset:640
	global_load_dwordx4 v[102:105], v34, s[26:27]
	global_load_dwordx4 v[106:109], v35, s[26:27]
	ds_read_b128 v[110:113], v36 offset:18496
	ds_read_b128 v[114:117], v36 offset:23104
	ds_read_b128 v[118:121], v33 offset:46144
	s_waitcnt vmcnt(11)
	ds_write_b128 v32, v[62:65]
	s_waitcnt vmcnt(10)
	ds_write_b128 v32, v[66:69] offset:4608
	s_waitcnt vmcnt(9)
	ds_write_b128 v32, v[70:73] offset:9216
	s_waitcnt vmcnt(8)
	ds_write_b128 v32, v[86:89] offset:13824
	s_waitcnt lgkmcnt(7)
	v_mfma_f32_32x32x16_bf16 v[16:31], v[74:77], v[82:85], v[16:31]
	v_mfma_f32_32x32x16_bf16 v[0:15], v[78:81], v[82:85], v[0:15]
	ds_read_b128 v[62:65], v36 offset:18528
	ds_read_b128 v[66:69], v36 offset:23136
	ds_read_b128 v[70:73], v33 offset:46176
	s_waitcnt vmcnt(7)
	ds_write_b128 v32, v[90:93] offset:36864
	s_waitcnt vmcnt(6)
	ds_write_b128 v32, v[94:97] offset:41472
	s_waitcnt lgkmcnt(0)
	s_barrier
	v_mfma_f32_32x32x16_bf16 v[16:31], v[110:113], v[118:121], v[16:31]
	v_mfma_f32_32x32x16_bf16 v[0:15], v[114:117], v[118:121], v[0:15]
	v_mfma_f32_32x32x16_bf16 v[16:31], v[62:65], v[70:73], v[16:31]
	v_mfma_f32_32x32x16_bf16 v[0:15], v[66:69], v[70:73], v[0:15]
	ds_read_b128 v[62:65], v36
	ds_read_b128 v[70:73], v36 offset:4608
	ds_read_b128 v[66:69], v33 offset:36864
	ds_read_b128 v[74:77], v36 offset:32
	ds_read_b128 v[78:81], v36 offset:4640
	ds_read_b128 v[82:85], v33 offset:36896
	s_waitcnt lgkmcnt(3)
	v_mfma_f32_32x32x16_bf16 v[16:31], v[62:65], v[66:69], v[16:31]
	v_mfma_f32_32x32x16_bf16 v[0:15], v[70:73], v[66:69], v[0:15]
	global_load_dwordx4 v[62:65], v34, vcc offset:768
	global_load_dwordx4 v[66:69], v35, vcc offset:768
	global_load_dwordx4 v[70:73], v38, vcc offset:768
	global_load_dwordx4 v[86:89], v39, vcc offset:768
	global_load_dwordx4 v[90:93], v34, s[28:29]
	global_load_dwordx4 v[94:97], v35, s[28:29]
	ds_read_b128 v[110:113], v36 offset:64
	ds_read_b128 v[114:117], v36 offset:4672
	ds_read_b128 v[118:121], v33 offset:36928
	s_waitcnt vmcnt(11)
	ds_write_b128 v32, v[46:49] offset:18432
	s_waitcnt vmcnt(10)
	ds_write_b128 v32, v[50:53] offset:23040
	s_waitcnt vmcnt(9)
	ds_write_b128 v32, v[58:61] offset:27648
	s_waitcnt vmcnt(8)
	ds_write_b128 v32, v[98:101] offset:32256
	s_waitcnt lgkmcnt(7)
	v_mfma_f32_32x32x16_bf16 v[16:31], v[74:77], v[82:85], v[16:31]
	v_mfma_f32_32x32x16_bf16 v[0:15], v[78:81], v[82:85], v[0:15]
	ds_read_b128 v[46:49], v36 offset:96
	ds_read_b128 v[50:53], v36 offset:4704
	ds_read_b128 v[58:61], v33 offset:36960
	s_waitcnt vmcnt(7)
	ds_write_b128 v32, v[102:105] offset:46080
	s_waitcnt vmcnt(6)
	ds_write_b128 v32, v[106:109] offset:50688
	s_waitcnt lgkmcnt(0)
	s_barrier
	v_mfma_f32_32x32x16_bf16 v[16:31], v[110:113], v[118:121], v[16:31]
	v_mfma_f32_32x32x16_bf16 v[0:15], v[114:117], v[118:121], v[0:15]
	v_mfma_f32_32x32x16_bf16 v[16:31], v[46:49], v[58:61], v[16:31]
	v_mfma_f32_32x32x16_bf16 v[0:15], v[50:53], v[58:61], v[0:15]
	ds_read_b128 v[46:49], v36 offset:18432
	ds_read_b128 v[58:61], v36 offset:23040
	ds_read_b128 v[50:53], v33 offset:46080
	ds_read_b128 v[74:77], v36 offset:18464
	ds_read_b128 v[78:81], v36 offset:23072
	ds_read_b128 v[82:85], v33 offset:46112
	s_waitcnt lgkmcnt(3)
	v_mfma_f32_32x32x16_bf16 v[16:31], v[46:49], v[50:53], v[16:31]
	v_mfma_f32_32x32x16_bf16 v[0:15], v[58:61], v[50:53], v[0:15]
	global_load_dwordx4 v[46:49], v34, vcc offset:896
	global_load_dwordx4 v[50:53], v35, vcc offset:896
	global_load_dwordx4 v[58:61], v38, vcc offset:896
	global_load_dwordx4 v[98:101], v39, vcc offset:896
	global_load_dwordx4 v[102:105], v34, s[30:31]
	global_load_dwordx4 v[106:109], v35, s[30:31]
	ds_read_b128 v[110:113], v36 offset:18496
	ds_read_b128 v[114:117], v36 offset:23104
	ds_read_b128 v[118:121], v33 offset:46144
	s_waitcnt vmcnt(11)
	ds_write_b128 v32, v[62:65]
	s_waitcnt vmcnt(10)
	ds_write_b128 v32, v[66:69] offset:4608
	s_waitcnt vmcnt(9)
	ds_write_b128 v32, v[70:73] offset:9216
	s_waitcnt vmcnt(8)
	ds_write_b128 v32, v[86:89] offset:13824
	s_waitcnt lgkmcnt(7)
	v_mfma_f32_32x32x16_bf16 v[16:31], v[74:77], v[82:85], v[16:31]
	v_mfma_f32_32x32x16_bf16 v[0:15], v[78:81], v[82:85], v[0:15]
	ds_read_b128 v[62:65], v36 offset:18528
	ds_read_b128 v[66:69], v36 offset:23136
	ds_read_b128 v[70:73], v33 offset:46176
	s_waitcnt vmcnt(7)
	ds_write_b128 v32, v[90:93] offset:36864
	s_waitcnt vmcnt(6)
	ds_write_b128 v32, v[94:97] offset:41472
	s_waitcnt lgkmcnt(0)
	s_barrier
	v_mfma_f32_32x32x16_bf16 v[16:31], v[110:113], v[118:121], v[16:31]
	v_mfma_f32_32x32x16_bf16 v[0:15], v[114:117], v[118:121], v[0:15]
	v_mfma_f32_32x32x16_bf16 v[16:31], v[62:65], v[70:73], v[16:31]
	v_mfma_f32_32x32x16_bf16 v[0:15], v[66:69], v[70:73], v[0:15]
	ds_read_b128 v[62:65], v36
	ds_read_b128 v[70:73], v36 offset:4608
	ds_read_b128 v[66:69], v33 offset:36864
	ds_read_b128 v[74:77], v36 offset:32
	ds_read_b128 v[78:81], v36 offset:4640
	ds_read_b128 v[82:85], v33 offset:36896
	s_waitcnt lgkmcnt(3)
	v_mfma_f32_32x32x16_bf16 v[16:31], v[62:65], v[66:69], v[16:31]
	v_mfma_f32_32x32x16_bf16 v[0:15], v[70:73], v[66:69], v[0:15]
	global_load_dwordx4 v[62:65], v34, vcc offset:1024
	global_load_dwordx4 v[66:69], v35, vcc offset:1024
	global_load_dwordx4 v[70:73], v38, vcc offset:1024
	global_load_dwordx4 v[86:89], v39, vcc offset:1024
	global_load_dwordx4 v[90:93], v34, s[34:35]
	global_load_dwordx4 v[94:97], v35, s[34:35]
	ds_read_b128 v[110:113], v36 offset:64
	ds_read_b128 v[114:117], v36 offset:4672
	ds_read_b128 v[118:121], v33 offset:36928
	s_waitcnt vmcnt(11)
	ds_write_b128 v32, v[46:49] offset:18432
	s_waitcnt vmcnt(10)
	ds_write_b128 v32, v[50:53] offset:23040
	s_waitcnt vmcnt(9)
	ds_write_b128 v32, v[58:61] offset:27648
	s_waitcnt vmcnt(8)
	ds_write_b128 v32, v[98:101] offset:32256
	s_waitcnt lgkmcnt(7)
	v_mfma_f32_32x32x16_bf16 v[16:31], v[74:77], v[82:85], v[16:31]
	v_mfma_f32_32x32x16_bf16 v[0:15], v[78:81], v[82:85], v[0:15]
	ds_read_b128 v[46:49], v36 offset:96
	ds_read_b128 v[50:53], v36 offset:4704
	ds_read_b128 v[58:61], v33 offset:36960
	s_waitcnt vmcnt(7)
	ds_write_b128 v32, v[102:105] offset:46080
	s_waitcnt vmcnt(6)
	ds_write_b128 v32, v[106:109] offset:50688
	s_waitcnt lgkmcnt(0)
	s_barrier
	v_mfma_f32_32x32x16_bf16 v[16:31], v[110:113], v[118:121], v[16:31]
	v_mfma_f32_32x32x16_bf16 v[0:15], v[114:117], v[118:121], v[0:15]
	v_mfma_f32_32x32x16_bf16 v[16:31], v[46:49], v[58:61], v[16:31]
	v_mfma_f32_32x32x16_bf16 v[0:15], v[50:53], v[58:61], v[0:15]
	ds_read_b128 v[46:49], v36 offset:18432
	ds_read_b128 v[58:61], v36 offset:23040
	ds_read_b128 v[50:53], v33 offset:46080
	ds_read_b128 v[74:77], v36 offset:18464
	ds_read_b128 v[78:81], v36 offset:23072
	ds_read_b128 v[82:85], v33 offset:46112
	s_waitcnt lgkmcnt(3)
	v_mfma_f32_32x32x16_bf16 v[16:31], v[46:49], v[50:53], v[16:31]
	v_mfma_f32_32x32x16_bf16 v[0:15], v[58:61], v[50:53], v[0:15]
	global_load_dwordx4 v[46:49], v34, vcc offset:1152
	global_load_dwordx4 v[50:53], v35, vcc offset:1152
	global_load_dwordx4 v[58:61], v38, vcc offset:1152
	global_load_dwordx4 v[98:101], v39, vcc offset:1152
	global_load_dwordx4 v[102:105], v34, s[14:15]
	global_load_dwordx4 v[106:109], v35, s[14:15]
	ds_read_b128 v[110:113], v36 offset:18496
	ds_read_b128 v[114:117], v36 offset:23104
	ds_read_b128 v[118:121], v33 offset:46144
	s_waitcnt vmcnt(11)
	ds_write_b128 v32, v[62:65]
	s_waitcnt vmcnt(10)
	ds_write_b128 v32, v[66:69] offset:4608
	s_waitcnt vmcnt(9)
	ds_write_b128 v32, v[70:73] offset:9216
	s_waitcnt vmcnt(8)
	ds_write_b128 v32, v[86:89] offset:13824
	s_waitcnt lgkmcnt(7)
	v_mfma_f32_32x32x16_bf16 v[16:31], v[74:77], v[82:85], v[16:31]
	v_mfma_f32_32x32x16_bf16 v[0:15], v[78:81], v[82:85], v[0:15]
	ds_read_b128 v[62:65], v36 offset:18528
	ds_read_b128 v[66:69], v36 offset:23136
	ds_read_b128 v[70:73], v33 offset:46176
	s_waitcnt vmcnt(7)
	ds_write_b128 v32, v[90:93] offset:36864
	s_waitcnt vmcnt(6)
	ds_write_b128 v32, v[94:97] offset:41472
	s_waitcnt lgkmcnt(0)
	s_barrier
	v_mfma_f32_32x32x16_bf16 v[16:31], v[110:113], v[118:121], v[16:31]
	v_mfma_f32_32x32x16_bf16 v[0:15], v[114:117], v[118:121], v[0:15]
	v_mfma_f32_32x32x16_bf16 v[16:31], v[62:65], v[70:73], v[16:31]
	v_mfma_f32_32x32x16_bf16 v[0:15], v[66:69], v[70:73], v[0:15]
	ds_read_b128 v[62:65], v36
	ds_read_b128 v[70:73], v36 offset:4608
	ds_read_b128 v[66:69], v33 offset:36864
	ds_read_b128 v[74:77], v36 offset:32
	ds_read_b128 v[78:81], v36 offset:4640
	ds_read_b128 v[82:85], v33 offset:36896
	s_waitcnt lgkmcnt(3)
	v_mfma_f32_32x32x16_bf16 v[16:31], v[62:65], v[66:69], v[16:31]
	v_mfma_f32_32x32x16_bf16 v[0:15], v[70:73], v[66:69], v[0:15]
	global_load_dwordx4 v[62:65], v34, vcc offset:1280
	global_load_dwordx4 v[66:69], v35, vcc offset:1280
	global_load_dwordx4 v[70:73], v38, vcc offset:1280
	global_load_dwordx4 v[86:89], v39, vcc offset:1280
	global_load_dwordx4 v[90:93], v34, s[52:53]
	global_load_dwordx4 v[94:97], v35, s[52:53]
	ds_read_b128 v[110:113], v36 offset:64
	ds_read_b128 v[114:117], v36 offset:4672
	ds_read_b128 v[118:121], v33 offset:36928
	s_waitcnt vmcnt(11)
	ds_write_b128 v32, v[46:49] offset:18432
	s_waitcnt vmcnt(10)
	ds_write_b128 v32, v[50:53] offset:23040
	s_waitcnt vmcnt(9)
	ds_write_b128 v32, v[58:61] offset:27648
	s_waitcnt vmcnt(8)
	ds_write_b128 v32, v[98:101] offset:32256
	s_waitcnt lgkmcnt(7)
	v_mfma_f32_32x32x16_bf16 v[16:31], v[74:77], v[82:85], v[16:31]
	v_mfma_f32_32x32x16_bf16 v[0:15], v[78:81], v[82:85], v[0:15]
	ds_read_b128 v[46:49], v36 offset:96
	ds_read_b128 v[50:53], v36 offset:4704
	ds_read_b128 v[58:61], v33 offset:36960
	s_waitcnt vmcnt(7)
	ds_write_b128 v32, v[102:105] offset:46080
	s_waitcnt vmcnt(6)
	ds_write_b128 v32, v[106:109] offset:50688
	s_waitcnt lgkmcnt(0)
	s_barrier
	v_mfma_f32_32x32x16_bf16 v[16:31], v[110:113], v[118:121], v[16:31]
	v_mfma_f32_32x32x16_bf16 v[0:15], v[114:117], v[118:121], v[0:15]
	v_mfma_f32_32x32x16_bf16 v[16:31], v[46:49], v[58:61], v[16:31]
	v_mfma_f32_32x32x16_bf16 v[0:15], v[50:53], v[58:61], v[0:15]
	ds_read_b128 v[46:49], v36 offset:18432
	ds_read_b128 v[58:61], v36 offset:23040
	ds_read_b128 v[50:53], v33 offset:46080
	ds_read_b128 v[74:77], v36 offset:18464
	ds_read_b128 v[78:81], v36 offset:23072
	ds_read_b128 v[82:85], v33 offset:46112
	s_waitcnt lgkmcnt(3)
	v_mfma_f32_32x32x16_bf16 v[16:31], v[46:49], v[50:53], v[16:31]
	v_mfma_f32_32x32x16_bf16 v[0:15], v[58:61], v[50:53], v[0:15]
	global_load_dwordx4 v[46:49], v34, vcc offset:1408
	global_load_dwordx4 v[50:53], v35, vcc offset:1408
	global_load_dwordx4 v[58:61], v38, vcc offset:1408
	global_load_dwordx4 v[98:101], v39, vcc offset:1408
	global_load_dwordx4 v[102:105], v34, s[96:97]
	global_load_dwordx4 v[106:109], v35, s[96:97]
	ds_read_b128 v[110:113], v36 offset:18496
	ds_read_b128 v[114:117], v36 offset:23104
	ds_read_b128 v[118:121], v33 offset:46144
	s_waitcnt vmcnt(11)
	ds_write_b128 v32, v[62:65]
	s_waitcnt vmcnt(10)
	ds_write_b128 v32, v[66:69] offset:4608
	s_waitcnt vmcnt(9)
	ds_write_b128 v32, v[70:73] offset:9216
	s_waitcnt vmcnt(8)
	ds_write_b128 v32, v[86:89] offset:13824
	s_waitcnt lgkmcnt(7)
	v_mfma_f32_32x32x16_bf16 v[16:31], v[74:77], v[82:85], v[16:31]
	v_mfma_f32_32x32x16_bf16 v[0:15], v[78:81], v[82:85], v[0:15]
	ds_read_b128 v[62:65], v36 offset:18528
	ds_read_b128 v[66:69], v36 offset:23136
	ds_read_b128 v[70:73], v33 offset:46176
	s_waitcnt vmcnt(7)
	ds_write_b128 v32, v[90:93] offset:36864
	s_waitcnt vmcnt(6)
	ds_write_b128 v32, v[94:97] offset:41472
	s_waitcnt lgkmcnt(0)
	s_barrier
	v_mfma_f32_32x32x16_bf16 v[16:31], v[110:113], v[118:121], v[16:31]
	v_mfma_f32_32x32x16_bf16 v[0:15], v[114:117], v[118:121], v[0:15]
	v_mfma_f32_32x32x16_bf16 v[16:31], v[62:65], v[70:73], v[16:31]
	v_mfma_f32_32x32x16_bf16 v[0:15], v[66:69], v[70:73], v[0:15]
	ds_read_b128 v[62:65], v36
	ds_read_b128 v[70:73], v36 offset:4608
	ds_read_b128 v[66:69], v33 offset:36864
	ds_read_b128 v[74:77], v36 offset:32
	ds_read_b128 v[78:81], v36 offset:4640
	ds_read_b128 v[82:85], v33 offset:36896
	s_waitcnt lgkmcnt(3)
	v_mfma_f32_32x32x16_bf16 v[16:31], v[62:65], v[66:69], v[16:31]
	v_mfma_f32_32x32x16_bf16 v[0:15], v[70:73], v[66:69], v[0:15]
	global_load_dwordx4 v[62:65], v34, vcc offset:1536
	global_load_dwordx4 v[66:69], v35, vcc offset:1536
	global_load_dwordx4 v[70:73], v38, vcc offset:1536
	global_load_dwordx4 v[86:89], v39, vcc offset:1536
	global_load_dwordx4 v[90:93], v34, s[68:69]
	global_load_dwordx4 v[94:97], v35, s[68:69]
	ds_read_b128 v[110:113], v36 offset:64
	ds_read_b128 v[114:117], v36 offset:4672
	ds_read_b128 v[118:121], v33 offset:36928
	s_waitcnt vmcnt(11)
	ds_write_b128 v32, v[46:49] offset:18432
	s_waitcnt vmcnt(10)
	ds_write_b128 v32, v[50:53] offset:23040
	s_waitcnt vmcnt(9)
	ds_write_b128 v32, v[58:61] offset:27648
	s_waitcnt vmcnt(8)
	ds_write_b128 v32, v[98:101] offset:32256
	s_waitcnt lgkmcnt(7)
	v_mfma_f32_32x32x16_bf16 v[16:31], v[74:77], v[82:85], v[16:31]
	v_mfma_f32_32x32x16_bf16 v[0:15], v[78:81], v[82:85], v[0:15]
	ds_read_b128 v[46:49], v36 offset:96
	ds_read_b128 v[50:53], v36 offset:4704
	ds_read_b128 v[58:61], v33 offset:36960
	s_waitcnt vmcnt(7)
	ds_write_b128 v32, v[102:105] offset:46080
	s_waitcnt vmcnt(6)
	ds_write_b128 v32, v[106:109] offset:50688
	s_waitcnt lgkmcnt(0)
	s_barrier
	v_mfma_f32_32x32x16_bf16 v[16:31], v[110:113], v[118:121], v[16:31]
	v_mfma_f32_32x32x16_bf16 v[0:15], v[114:117], v[118:121], v[0:15]
	v_mfma_f32_32x32x16_bf16 v[16:31], v[46:49], v[58:61], v[16:31]
	v_mfma_f32_32x32x16_bf16 v[0:15], v[50:53], v[58:61], v[0:15]
	ds_read_b128 v[46:49], v36 offset:18432
	ds_read_b128 v[58:61], v36 offset:23040
	ds_read_b128 v[50:53], v33 offset:46080
	ds_read_b128 v[74:77], v36 offset:18464
	ds_read_b128 v[78:81], v36 offset:23072
	ds_read_b128 v[82:85], v33 offset:46112
	s_waitcnt lgkmcnt(3)
	v_mfma_f32_32x32x16_bf16 v[16:31], v[46:49], v[50:53], v[16:31]
	v_mfma_f32_32x32x16_bf16 v[0:15], v[58:61], v[50:53], v[0:15]
	global_load_dwordx4 v[46:49], v34, vcc offset:1664
	global_load_dwordx4 v[50:53], v35, vcc offset:1664
	global_load_dwordx4 v[58:61], v38, vcc offset:1664
	global_load_dwordx4 v[98:101], v39, vcc offset:1664
	global_load_dwordx4 v[102:105], v34, s[70:71]
	global_load_dwordx4 v[106:109], v35, s[70:71]
	ds_read_b128 v[110:113], v36 offset:18496
	ds_read_b128 v[114:117], v36 offset:23104
	ds_read_b128 v[118:121], v33 offset:46144
	s_waitcnt vmcnt(11)
	ds_write_b128 v32, v[62:65]
	s_waitcnt vmcnt(10)
	ds_write_b128 v32, v[66:69] offset:4608
	s_waitcnt vmcnt(9)
	ds_write_b128 v32, v[70:73] offset:9216
	s_waitcnt vmcnt(8)
	ds_write_b128 v32, v[86:89] offset:13824
	s_waitcnt lgkmcnt(7)
	v_mfma_f32_32x32x16_bf16 v[16:31], v[74:77], v[82:85], v[16:31]
	v_mfma_f32_32x32x16_bf16 v[0:15], v[78:81], v[82:85], v[0:15]
	ds_read_b128 v[62:65], v36 offset:18528
	ds_read_b128 v[66:69], v36 offset:23136
	ds_read_b128 v[70:73], v33 offset:46176
	s_waitcnt vmcnt(7)
	ds_write_b128 v32, v[90:93] offset:36864
	s_waitcnt vmcnt(6)
	ds_write_b128 v32, v[94:97] offset:41472
	s_waitcnt lgkmcnt(0)
	s_barrier
	v_mfma_f32_32x32x16_bf16 v[16:31], v[110:113], v[118:121], v[16:31]
	v_mfma_f32_32x32x16_bf16 v[0:15], v[114:117], v[118:121], v[0:15]
	v_mfma_f32_32x32x16_bf16 v[16:31], v[62:65], v[70:73], v[16:31]
	v_mfma_f32_32x32x16_bf16 v[0:15], v[66:69], v[70:73], v[0:15]
	ds_read_b128 v[62:65], v36
	ds_read_b128 v[70:73], v36 offset:4608
	ds_read_b128 v[66:69], v33 offset:36864
	ds_read_b128 v[74:77], v36 offset:32
	ds_read_b128 v[78:81], v36 offset:4640
	ds_read_b128 v[82:85], v33 offset:36896
	s_waitcnt lgkmcnt(3)
	v_mfma_f32_32x32x16_bf16 v[16:31], v[62:65], v[66:69], v[16:31]
	v_mfma_f32_32x32x16_bf16 v[0:15], v[70:73], v[66:69], v[0:15]
	global_load_dwordx4 v[62:65], v34, vcc offset:1792
	global_load_dwordx4 v[66:69], v35, vcc offset:1792
	global_load_dwordx4 v[70:73], v38, vcc offset:1792
	global_load_dwordx4 v[86:89], v39, vcc offset:1792
	global_load_dwordx4 v[90:93], v34, s[72:73]
	global_load_dwordx4 v[94:97], v35, s[72:73]
	ds_read_b128 v[110:113], v36 offset:64
	ds_read_b128 v[114:117], v36 offset:4672
	ds_read_b128 v[118:121], v33 offset:36928
	s_waitcnt vmcnt(11)
	ds_write_b128 v32, v[46:49] offset:18432
	s_waitcnt vmcnt(10)
	ds_write_b128 v32, v[50:53] offset:23040
	s_waitcnt vmcnt(9)
	ds_write_b128 v32, v[58:61] offset:27648
	s_waitcnt vmcnt(8)
	ds_write_b128 v32, v[98:101] offset:32256
	s_waitcnt lgkmcnt(7)
	v_mfma_f32_32x32x16_bf16 v[16:31], v[74:77], v[82:85], v[16:31]
	v_mfma_f32_32x32x16_bf16 v[0:15], v[78:81], v[82:85], v[0:15]
	ds_read_b128 v[46:49], v36 offset:96
	ds_read_b128 v[50:53], v36 offset:4704
	ds_read_b128 v[58:61], v33 offset:36960
	s_waitcnt vmcnt(7)
	ds_write_b128 v32, v[102:105] offset:46080
	s_waitcnt vmcnt(6)
	ds_write_b128 v32, v[106:109] offset:50688
	s_waitcnt lgkmcnt(0)
	s_barrier
	v_mfma_f32_32x32x16_bf16 v[16:31], v[110:113], v[118:121], v[16:31]
	v_mfma_f32_32x32x16_bf16 v[0:15], v[114:117], v[118:121], v[0:15]
	v_mfma_f32_32x32x16_bf16 v[16:31], v[46:49], v[58:61], v[16:31]
	v_mfma_f32_32x32x16_bf16 v[0:15], v[50:53], v[58:61], v[0:15]
	ds_read_b128 v[58:61], v36 offset:23040
	ds_read_b128 v[50:53], v33 offset:46080
	ds_read_b128 v[46:49], v36 offset:18432
	ds_read_b128 v[78:81], v36 offset:23072
	ds_read_b128 v[74:77], v36 offset:18464
	ds_read_b128 v[82:85], v33 offset:46112
	s_waitcnt lgkmcnt(4)
	v_mfma_f32_32x32x16_bf16 v[0:15], v[58:61], v[50:53], v[0:15]
	s_waitcnt lgkmcnt(3)
	v_mfma_f32_32x32x16_bf16 v[16:31], v[46:49], v[50:53], v[16:31]
	global_load_dwordx4 v[46:49], v34, vcc offset:1920
	global_load_dwordx4 v[50:53], v35, vcc offset:1920
	global_load_dwordx4 v[58:61], v38, vcc offset:1920
	global_load_dwordx4 v[98:101], v39, vcc offset:1920
	global_load_dwordx4 v[102:105], v34, s[74:75]
	global_load_dwordx4 v[106:109], v35, s[74:75]
	ds_read_b128 v[114:117], v36 offset:23104
	ds_read_b128 v[110:113], v36 offset:18496
	ds_read_b128 v[118:121], v33 offset:46144
	s_waitcnt vmcnt(11)
	ds_write_b128 v32, v[62:65]
	s_waitcnt vmcnt(10)
	ds_write_b128 v32, v[66:69] offset:4608
	s_waitcnt vmcnt(9)
	ds_write_b128 v32, v[70:73] offset:9216
	s_waitcnt vmcnt(8)
	ds_write_b128 v32, v[86:89] offset:13824
	s_waitcnt lgkmcnt(7)
	v_mfma_f32_32x32x16_bf16 v[0:15], v[78:81], v[82:85], v[0:15]
	ds_read_b128 v[66:69], v36 offset:23136
	ds_read_b128 v[62:65], v36 offset:18528
	ds_read_b128 v[70:73], v33 offset:46176
	s_waitcnt vmcnt(7)
	ds_write_b128 v32, v[90:93] offset:36864
	s_waitcnt vmcnt(6)
	ds_write_b128 v32, v[94:97] offset:41472
	s_waitcnt lgkmcnt(0)
	s_barrier
	v_mfma_f32_32x32x16_bf16 v[0:15], v[114:117], v[118:121], v[0:15]
	v_mfma_f32_32x32x16_bf16 v[0:15], v[66:69], v[70:73], v[0:15]
	ds_read_b128 v[66:69], v33 offset:36864
	v_mfma_f32_32x32x16_bf16 v[16:31], v[74:77], v[82:85], v[16:31]
	v_mfma_f32_32x32x16_bf16 v[16:31], v[110:113], v[118:121], v[16:31]
	v_mfma_f32_32x32x16_bf16 v[16:31], v[62:65], v[70:73], v[16:31]
	ds_read_b128 v[62:65], v36
	s_waitcnt lgkmcnt(0)
	v_mfma_f32_32x32x16_bf16 v[16:31], v[62:65], v[66:69], v[16:31]
	ds_read_b128 v[62:65], v36 offset:4608
	s_waitcnt lgkmcnt(0)
	v_mfma_f32_32x32x16_bf16 v[0:15], v[62:65], v[66:69], v[0:15]
	ds_read_b128 v[62:65], v36 offset:32
	ds_read_b128 v[66:69], v33 offset:36896
	s_waitcnt lgkmcnt(0)
	v_mfma_f32_32x32x16_bf16 v[16:31], v[62:65], v[66:69], v[16:31]
	ds_read_b128 v[62:65], v36 offset:4640
	s_waitcnt lgkmcnt(0)
	v_mfma_f32_32x32x16_bf16 v[0:15], v[62:65], v[66:69], v[0:15]
	ds_read_b128 v[62:65], v36 offset:64
	ds_read_b128 v[66:69], v33 offset:36928
	s_waitcnt lgkmcnt(0)
	v_mfma_f32_32x32x16_bf16 v[16:31], v[62:65], v[66:69], v[16:31]
	ds_read_b128 v[62:65], v36 offset:4672
	s_waitcnt vmcnt(3)
	ds_write_b128 v32, v[58:61] offset:27648
	s_waitcnt vmcnt(2)
	ds_write_b128 v32, v[98:101] offset:32256
	ds_write_b128 v32, v[46:49] offset:18432
	ds_write_b128 v32, v[50:53] offset:23040
	ds_read_b128 v[46:49], v36 offset:96
	ds_read_b128 v[50:53], v33 offset:36960
	s_waitcnt lgkmcnt(0)
	v_mfma_f32_32x32x16_bf16 v[16:31], v[46:49], v[50:53], v[16:31]
	ds_read_b128 v[46:49], v36 offset:4704
	v_add_u32_e32 v58, s41, v57
	v_add_u32_e32 v45, 0xffffe000, v58
	v_mfma_f32_32x32x16_bf16 v[0:15], v[62:65], v[66:69], v[0:15]
	s_waitcnt lgkmcnt(0)
	v_mfma_f32_32x32x16_bf16 v[0:15], v[46:49], v[50:53], v[0:15]
	s_waitcnt vmcnt(1)
	ds_write_b128 v32, v[102:105] offset:46080
	s_waitcnt vmcnt(0)
	ds_write_b128 v32, v[106:109] offset:50688
	s_waitcnt lgkmcnt(0)
	s_barrier
	ds_read_b128 v[46:49], v36 offset:18432
	ds_read_b128 v[50:53], v33 offset:46080
	s_waitcnt lgkmcnt(0)
	v_mfma_f32_32x32x16_bf16 v[16:31], v[46:49], v[50:53], v[16:31]
	ds_read_b128 v[46:49], v36 offset:23040
	s_waitcnt lgkmcnt(0)
	v_mfma_f32_32x32x16_bf16 v[0:15], v[46:49], v[50:53], v[0:15]
	ds_read_b128 v[46:49], v36 offset:18464
	ds_read_b128 v[50:53], v33 offset:46112
	s_waitcnt lgkmcnt(0)
	v_mfma_f32_32x32x16_bf16 v[16:31], v[46:49], v[50:53], v[16:31]
	ds_read_b128 v[46:49], v36 offset:23072
	s_waitcnt lgkmcnt(0)
	v_mfma_f32_32x32x16_bf16 v[0:15], v[46:49], v[50:53], v[0:15]
	ds_read_b128 v[46:49], v36 offset:18496
	ds_read_b128 v[50:53], v33 offset:46144
	ds_read_b128 v[32:35], v33 offset:46176
	s_waitcnt lgkmcnt(1)
	v_mfma_f32_32x32x16_bf16 v[16:31], v[46:49], v[50:53], v[16:31]
	ds_read_b128 v[46:49], v36 offset:23104
	s_waitcnt lgkmcnt(0)
	v_mfma_f32_32x32x16_bf16 v[0:15], v[46:49], v[50:53], v[0:15]
	ds_read_b128 v[46:49], v36 offset:18528
	ds_read_b128 v[36:39], v36 offset:23136
	s_waitcnt lgkmcnt(0)
	s_barrier
	v_mfma_f32_32x32x16_bf16 v[16:31], v[46:49], v[32:35], v[16:31]
	v_mfma_f32_32x32x16_bf16 v[0:15], v[36:39], v[32:35], v[0:15]
	v_readfirstlane_b32 s13, v186
	v_and_b32_e32 v32, 63, v186
	v_and_b32_e32 v33, 31, v32
	v_lshrrev_b32_e32 v34, 5, v32
	s_lshr_b32 s13, s13, 6
	s_and_b32 s32, s13, 1
	s_mul_i32 s80, s13, 0x1400
	s_lshr_b32 s13, s13, 1
	s_lshl_b32 s13, s13, 6
	s_add_i32 s33, s41, 0xffffe000
	s_add_i32 s81, s13, s33
	v_lshl_add_u32 v35, v34, 2, s81
	s_cmp_lg_u32 s32, 0
	s_cbranch_scc1 .Lp3a_gate
	v_and_b32_e32 v36, 15, v33
	v_lshlrev_b32_e32 v37, 6, v35
	v_lshl_add_u32 v37, v36, 2, v37
	v_xor_b32_e32 v38, 16, v32
	v_lshlrev_b32_e32 v38, 2, v38
	global_load_dword v84, v37, s[0:1]
	global_load_dword v116, v37, s[8:9]
	global_load_dword v85, v37, s[0:1] offset:64
	global_load_dword v117, v37, s[8:9] offset:64
	global_load_dword v86, v37, s[0:1] offset:128
	global_load_dword v118, v37, s[8:9] offset:128
	global_load_dword v87, v37, s[0:1] offset:192
	global_load_dword v119, v37, s[8:9] offset:192
	global_load_dword v88, v37, s[0:1] offset:512
	global_load_dword v120, v37, s[8:9] offset:512
	global_load_dword v89, v37, s[0:1] offset:576
	global_load_dword v121, v37, s[8:9] offset:576
	global_load_dword v90, v37, s[0:1] offset:640
	global_load_dword v122, v37, s[8:9] offset:640
	global_load_dword v91, v37, s[0:1] offset:704
	global_load_dword v123, v37, s[8:9] offset:704
	global_load_dword v92, v37, s[0:1] offset:1024
	global_load_dword v124, v37, s[8:9] offset:1024
	global_load_dword v93, v37, s[0:1] offset:1088
	global_load_dword v125, v37, s[8:9] offset:1088
	global_load_dword v94, v37, s[0:1] offset:1152
	global_load_dword v126, v37, s[8:9] offset:1152
	global_load_dword v95, v37, s[0:1] offset:1216
	global_load_dword v127, v37, s[8:9] offset:1216
	global_load_dword v96, v37, s[0:1] offset:1536
	global_load_dword v128, v37, s[8:9] offset:1536
	global_load_dword v97, v37, s[0:1] offset:1600
	global_load_dword v129, v37, s[8:9] offset:1600
	global_load_dword v98, v37, s[0:1] offset:1664
	global_load_dword v130, v37, s[8:9] offset:1664
	global_load_dword v99, v37, s[0:1] offset:1728
	global_load_dword v131, v37, s[8:9] offset:1728
	global_load_dword v100, v37, s[0:1] offset:2048
	global_load_dword v132, v37, s[8:9] offset:2048
	global_load_dword v101, v37, s[0:1] offset:2112
	global_load_dword v133, v37, s[8:9] offset:2112
	global_load_dword v102, v37, s[0:1] offset:2176
	global_load_dword v134, v37, s[8:9] offset:2176
	global_load_dword v103, v37, s[0:1] offset:2240
	global_load_dword v135, v37, s[8:9] offset:2240
	global_load_dword v104, v37, s[0:1] offset:2560
	global_load_dword v136, v37, s[8:9] offset:2560
	global_load_dword v105, v37, s[0:1] offset:2624
	global_load_dword v137, v37, s[8:9] offset:2624
	global_load_dword v106, v37, s[0:1] offset:2688
	global_load_dword v138, v37, s[8:9] offset:2688
	global_load_dword v107, v37, s[0:1] offset:2752
	global_load_dword v139, v37, s[8:9] offset:2752
	global_load_dword v108, v37, s[0:1] offset:3072
	global_load_dword v140, v37, s[8:9] offset:3072
	global_load_dword v109, v37, s[0:1] offset:3136
	global_load_dword v141, v37, s[8:9] offset:3136
	global_load_dword v110, v37, s[0:1] offset:3200
	global_load_dword v142, v37, s[8:9] offset:3200
	global_load_dword v111, v37, s[0:1] offset:3264
	global_load_dword v143, v37, s[8:9] offset:3264
	global_load_dword v112, v37, s[0:1] offset:3584
	global_load_dword v144, v37, s[8:9] offset:3584
	global_load_dword v113, v37, s[0:1] offset:3648
	global_load_dword v145, v37, s[8:9] offset:3648
	global_load_dword v114, v37, s[0:1] offset:3712
	global_load_dword v146, v37, s[8:9] offset:3712
	global_load_dword v115, v37, s[0:1] offset:3776
	global_load_dword v147, v37, s[8:9] offset:3776
	v_mul_u32_u24_e32 v76, 0x140, v34
	v_lshl_add_u32 v76, v33, 1, v76
	v_add_u32_e32 v76, s80, v76
	v_lshrrev_b32_e32 v77, 2, v32
	v_and_b32_e32 v78, 3, v32
	v_mul_u32_u24_e32 v80, 0x50, v77
	v_lshl_add_u32 v80, v78, 4, v80
	v_add_u32_e32 v80, s80, v80
	s_and_b32 s32, s81, 0x1fff
	v_add_u32_e32 v39, s32, v77
	v_mul_u32_u24_e32 v39, 0xc0, v39
	v_lshl_add_u32 v39, v78, 4, v39
	v_add_u32_e32 v39, 0x80, v39
	s_lshr_b32 s13, s33, 13
	s_mul_i32 s13, s13, 0xc00000
	s_add_u32 s13, s13, 0xb200000
	s_add_u32 s78, s88, s13
	s_addc_u32 s79, s89, 0
	ds_bpermute_b32 v148, v38, v16
	ds_bpermute_b32 v149, v38, v17
	ds_bpermute_b32 v150, v38, v18
	ds_bpermute_b32 v151, v38, v19
	ds_bpermute_b32 v152, v38, v20
	ds_bpermute_b32 v153, v38, v21
	ds_bpermute_b32 v154, v38, v22
	ds_bpermute_b32 v155, v38, v23
	s_waitcnt vmcnt(0) lgkmcnt(0)
	v_mul_f32_e32 v46, v116, v148
	v_cndmask_b32_e64 v46, v46, -v46, s[6:7]
	v_fmac_f32_e32 v46, v16, v84
	v_cvt_pk_bf16_f32 v46, v46, v46
	ds_write_b16 v76, v46
	v_mul_f32_e32 v47, v117, v149
	v_cndmask_b32_e64 v47, v47, -v47, s[6:7]
	v_fmac_f32_e32 v47, v17, v85
	v_cvt_pk_bf16_f32 v47, v47, v47
	ds_write_b16 v76, v47 offset:80
	v_mul_f32_e32 v48, v118, v150
	v_cndmask_b32_e64 v48, v48, -v48, s[6:7]
	v_fmac_f32_e32 v48, v18, v86
	v_cvt_pk_bf16_f32 v48, v48, v48
	ds_write_b16 v76, v48 offset:160
	v_mul_f32_e32 v49, v119, v151
	v_cndmask_b32_e64 v49, v49, -v49, s[6:7]
	v_fmac_f32_e32 v49, v19, v87
	v_cvt_pk_bf16_f32 v49, v49, v49
	ds_write_b16 v76, v49 offset:240
	v_mul_f32_e32 v46, v120, v152
	v_cndmask_b32_e64 v46, v46, -v46, s[6:7]
	v_fmac_f32_e32 v46, v20, v88
	v_cvt_pk_bf16_f32 v46, v46, v46
	ds_write_b16 v76, v46 offset:640
	v_mul_f32_e32 v47, v121, v153
	v_cndmask_b32_e64 v47, v47, -v47, s[6:7]
	v_fmac_f32_e32 v47, v21, v89
	v_cvt_pk_bf16_f32 v47, v47, v47
	ds_write_b16 v76, v47 offset:720
	v_mul_f32_e32 v48, v122, v154
	v_cndmask_b32_e64 v48, v48, -v48, s[6:7]
	v_fmac_f32_e32 v48, v22, v90
	v_cvt_pk_bf16_f32 v48, v48, v48
	ds_write_b16 v76, v48 offset:800
	v_mul_f32_e32 v49, v123, v155
	v_cndmask_b32_e64 v49, v49, -v49, s[6:7]
	v_fmac_f32_e32 v49, v23, v91
	v_cvt_pk_bf16_f32 v49, v49, v49
	ds_write_b16 v76, v49 offset:880
	ds_bpermute_b32 v148, v38, v24
	ds_bpermute_b32 v149, v38, v25
	ds_bpermute_b32 v150, v38, v26
	ds_bpermute_b32 v151, v38, v27
	ds_bpermute_b32 v152, v38, v28
	ds_bpermute_b32 v153, v38, v29
	ds_bpermute_b32 v154, v38, v30
	ds_bpermute_b32 v155, v38, v31
	s_waitcnt lgkmcnt(0)
	v_mul_f32_e32 v46, v124, v148
	v_cndmask_b32_e64 v46, v46, -v46, s[6:7]
	v_fmac_f32_e32 v46, v24, v92
	v_cvt_pk_bf16_f32 v46, v46, v46
	ds_write_b16 v76, v46 offset:1280
	v_mul_f32_e32 v47, v125, v149
	v_cndmask_b32_e64 v47, v47, -v47, s[6:7]
	v_fmac_f32_e32 v47, v25, v93
	v_cvt_pk_bf16_f32 v47, v47, v47
	ds_write_b16 v76, v47 offset:1360
	v_mul_f32_e32 v48, v126, v150
	v_cndmask_b32_e64 v48, v48, -v48, s[6:7]
	v_fmac_f32_e32 v48, v26, v94
	v_cvt_pk_bf16_f32 v48, v48, v48
	ds_write_b16 v76, v48 offset:1440
	v_mul_f32_e32 v49, v127, v151
	v_cndmask_b32_e64 v49, v49, -v49, s[6:7]
	v_fmac_f32_e32 v49, v27, v95
	v_cvt_pk_bf16_f32 v49, v49, v49
	ds_write_b16 v76, v49 offset:1520
	v_mul_f32_e32 v46, v128, v152
	v_cndmask_b32_e64 v46, v46, -v46, s[6:7]
	v_fmac_f32_e32 v46, v28, v96
	v_cvt_pk_bf16_f32 v46, v46, v46
	ds_write_b16 v76, v46 offset:1920
	v_mul_f32_e32 v47, v129, v153
	v_cndmask_b32_e64 v47, v47, -v47, s[6:7]
	v_fmac_f32_e32 v47, v29, v97
	v_cvt_pk_bf16_f32 v47, v47, v47
	ds_write_b16 v76, v47 offset:2000
	v_mul_f32_e32 v48, v130, v154
	v_cndmask_b32_e64 v48, v48, -v48, s[6:7]
	v_fmac_f32_e32 v48, v30, v98
	v_cvt_pk_bf16_f32 v48, v48, v48
	ds_write_b16 v76, v48 offset:2080
	v_mul_f32_e32 v49, v131, v155
	v_cndmask_b32_e64 v49, v49, -v49, s[6:7]
	v_fmac_f32_e32 v49, v31, v99
	v_cvt_pk_bf16_f32 v49, v49, v49
	ds_write_b16 v76, v49 offset:2160
	ds_bpermute_b32 v148, v38, v0
	ds_bpermute_b32 v149, v38, v1
	ds_bpermute_b32 v150, v38, v2
	ds_bpermute_b32 v151, v38, v3
	ds_bpermute_b32 v152, v38, v4
	ds_bpermute_b32 v153, v38, v5
	ds_bpermute_b32 v154, v38, v6
	ds_bpermute_b32 v155, v38, v7
	s_waitcnt lgkmcnt(0)
	v_mul_f32_e32 v46, v132, v148
	v_cndmask_b32_e64 v46, v46, -v46, s[6:7]
	v_fmac_f32_e32 v46, v0, v100
	v_cvt_pk_bf16_f32 v46, v46, v46
	ds_write_b16 v76, v46 offset:2560
	v_mul_f32_e32 v47, v133, v149
	v_cndmask_b32_e64 v47, v47, -v47, s[6:7]
	v_fmac_f32_e32 v47, v1, v101
	v_cvt_pk_bf16_f32 v47, v47, v47
	ds_write_b16 v76, v47 offset:2640
	v_mul_f32_e32 v48, v134, v150
	v_cndmask_b32_e64 v48, v48, -v48, s[6:7]
	v_fmac_f32_e32 v48, v2, v102
	v_cvt_pk_bf16_f32 v48, v48, v48
	ds_write_b16 v76, v48 offset:2720
	v_mul_f32_e32 v49, v135, v151
	v_cndmask_b32_e64 v49, v49, -v49, s[6:7]
	v_fmac_f32_e32 v49, v3, v103
	v_cvt_pk_bf16_f32 v49, v49, v49
	ds_write_b16 v76, v49 offset:2800
	v_mul_f32_e32 v46, v136, v152
	v_cndmask_b32_e64 v46, v46, -v46, s[6:7]
	v_fmac_f32_e32 v46, v4, v104
	v_cvt_pk_bf16_f32 v46, v46, v46
	ds_write_b16 v76, v46 offset:3200
	v_mul_f32_e32 v47, v137, v153
	v_cndmask_b32_e64 v47, v47, -v47, s[6:7]
	v_fmac_f32_e32 v47, v5, v105
	v_cvt_pk_bf16_f32 v47, v47, v47
	ds_write_b16 v76, v47 offset:3280
	v_mul_f32_e32 v48, v138, v154
	v_cndmask_b32_e64 v48, v48, -v48, s[6:7]
	v_fmac_f32_e32 v48, v6, v106
	v_cvt_pk_bf16_f32 v48, v48, v48
	ds_write_b16 v76, v48 offset:3360
	v_mul_f32_e32 v49, v139, v155
	v_cndmask_b32_e64 v49, v49, -v49, s[6:7]
	v_fmac_f32_e32 v49, v7, v107
	v_cvt_pk_bf16_f32 v49, v49, v49
	ds_write_b16 v76, v49 offset:3440
	ds_bpermute_b32 v148, v38, v8
	ds_bpermute_b32 v149, v38, v9
	ds_bpermute_b32 v150, v38, v10
	ds_bpermute_b32 v151, v38, v11
	ds_bpermute_b32 v152, v38, v12
	ds_bpermute_b32 v153, v38, v13
	ds_bpermute_b32 v154, v38, v14
	ds_bpermute_b32 v155, v38, v15
	s_waitcnt lgkmcnt(0)
	v_mul_f32_e32 v46, v140, v148
	v_cndmask_b32_e64 v46, v46, -v46, s[6:7]
	v_fmac_f32_e32 v46, v8, v108
	v_cvt_pk_bf16_f32 v46, v46, v46
	ds_write_b16 v76, v46 offset:3840
	v_mul_f32_e32 v47, v141, v149
	v_cndmask_b32_e64 v47, v47, -v47, s[6:7]
	v_fmac_f32_e32 v47, v9, v109
	v_cvt_pk_bf16_f32 v47, v47, v47
	ds_write_b16 v76, v47 offset:3920
	v_mul_f32_e32 v48, v142, v150
	v_cndmask_b32_e64 v48, v48, -v48, s[6:7]
	v_fmac_f32_e32 v48, v10, v110
	v_cvt_pk_bf16_f32 v48, v48, v48
	ds_write_b16 v76, v48 offset:4000
	v_mul_f32_e32 v49, v143, v151
	v_cndmask_b32_e64 v49, v49, -v49, s[6:7]
	v_fmac_f32_e32 v49, v11, v111
	v_cvt_pk_bf16_f32 v49, v49, v49
	ds_write_b16 v76, v49 offset:4080
	v_mul_f32_e32 v46, v144, v152
	v_cndmask_b32_e64 v46, v46, -v46, s[6:7]
	v_fmac_f32_e32 v46, v12, v112
	v_cvt_pk_bf16_f32 v46, v46, v46
	ds_write_b16 v76, v46 offset:4480
	v_mul_f32_e32 v47, v145, v153
	v_cndmask_b32_e64 v47, v47, -v47, s[6:7]
	v_fmac_f32_e32 v47, v13, v113
	v_cvt_pk_bf16_f32 v47, v47, v47
	ds_write_b16 v76, v47 offset:4560
	v_mul_f32_e32 v48, v146, v154
	v_cndmask_b32_e64 v48, v48, -v48, s[6:7]
	v_fmac_f32_e32 v48, v14, v114
	v_cvt_pk_bf16_f32 v48, v48, v48
	ds_write_b16 v76, v48 offset:4640
	v_mul_f32_e32 v49, v147, v155
	v_cndmask_b32_e64 v49, v49, -v49, s[6:7]
	v_fmac_f32_e32 v49, v15, v115
	v_cvt_pk_bf16_f32 v49, v49, v49
	ds_write_b16 v76, v49 offset:4720
	s_waitcnt lgkmcnt(0)
	ds_read_b128 v[60:63], v80
	ds_read_b128 v[64:67], v80 offset:1280
	ds_read_b128 v[68:71], v80 offset:2560
	ds_read_b128 v[72:75], v80 offset:3840
	s_waitcnt lgkmcnt(0)
	global_store_dwordx4 v39, v[60:63], s[78:79] sc0 sc1
	v_add_u32_e32 v51, 0xc00, v39
	global_store_dwordx4 v51, v[64:67], s[78:79] sc0 sc1
	v_add_u32_e32 v50, 0x1800, v39
	global_store_dwordx4 v50, v[68:71], s[78:79] sc0 sc1
	v_add_u32_e32 v51, 0x2400, v39
	global_store_dwordx4 v51, v[72:75], s[78:79] sc0 sc1
	v_add_u32_e32 v50, 0x180000, v39
	global_store_dwordx4 v50, v[60:63], s[78:79] sc0 sc1
	v_add_u32_e32 v51, 0x180c00, v39
	global_store_dwordx4 v51, v[64:67], s[78:79] sc0 sc1
	v_add_u32_e32 v50, 0x181800, v39
	global_store_dwordx4 v50, v[68:71], s[78:79] sc0 sc1
	v_add_u32_e32 v51, 0x182400, v39
	global_store_dwordx4 v51, v[72:75], s[78:79] sc0 sc1
	v_add_u32_e32 v50, 0x300000, v39
	global_store_dwordx4 v50, v[60:63], s[78:79] sc0 sc1
	v_add_u32_e32 v51, 0x300c00, v39
	global_store_dwordx4 v51, v[64:67], s[78:79] sc0 sc1
	v_add_u32_e32 v50, 0x301800, v39
	global_store_dwordx4 v50, v[68:71], s[78:79] sc0 sc1
	v_add_u32_e32 v51, 0x302400, v39
	global_store_dwordx4 v51, v[72:75], s[78:79] sc0 sc1
	v_add_u32_e32 v50, 0x480000, v39
	global_store_dwordx4 v50, v[60:63], s[78:79] sc0 sc1
	v_add_u32_e32 v51, 0x480c00, v39
	global_store_dwordx4 v51, v[64:67], s[78:79] sc0 sc1
	v_add_u32_e32 v50, 0x481800, v39
	global_store_dwordx4 v50, v[68:71], s[78:79] sc0 sc1
	v_add_u32_e32 v51, 0x482400, v39
	global_store_dwordx4 v51, v[72:75], s[78:79] sc0 sc1
	v_add_u32_e32 v50, 0x600000, v39
	global_store_dwordx4 v50, v[60:63], s[78:79] sc0 sc1
	v_add_u32_e32 v51, 0x600c00, v39
	global_store_dwordx4 v51, v[64:67], s[78:79] sc0 sc1
	v_add_u32_e32 v50, 0x601800, v39
	global_store_dwordx4 v50, v[68:71], s[78:79] sc0 sc1
	v_add_u32_e32 v51, 0x602400, v39
	global_store_dwordx4 v51, v[72:75], s[78:79] sc0 sc1
	v_add_u32_e32 v50, 0x780000, v39
	global_store_dwordx4 v50, v[60:63], s[78:79] sc0 sc1
	v_add_u32_e32 v51, 0x780c00, v39
	global_store_dwordx4 v51, v[64:67], s[78:79] sc0 sc1
	v_add_u32_e32 v50, 0x781800, v39
	global_store_dwordx4 v50, v[68:71], s[78:79] sc0 sc1
	v_add_u32_e32 v51, 0x782400, v39
	global_store_dwordx4 v51, v[72:75], s[78:79] sc0 sc1
	v_add_u32_e32 v50, 0x900000, v39
	global_store_dwordx4 v50, v[60:63], s[78:79] sc0 sc1
	v_add_u32_e32 v51, 0x900c00, v39
	global_store_dwordx4 v51, v[64:67], s[78:79] sc0 sc1
	v_add_u32_e32 v50, 0x901800, v39
	global_store_dwordx4 v50, v[68:71], s[78:79] sc0 sc1
	v_add_u32_e32 v51, 0x902400, v39
	global_store_dwordx4 v51, v[72:75], s[78:79] sc0 sc1
	v_add_u32_e32 v50, 0xa80000, v39
	global_store_dwordx4 v50, v[60:63], s[78:79] sc0 sc1
	v_add_u32_e32 v51, 0xa80c00, v39
	global_store_dwordx4 v51, v[64:67], s[78:79] sc0 sc1
	v_add_u32_e32 v50, 0xa81800, v39
	global_store_dwordx4 v50, v[68:71], s[78:79] sc0 sc1
	v_add_u32_e32 v51, 0xa82400, v39
	global_store_dwordx4 v51, v[72:75], s[78:79] sc0 sc1
	s_branch .Lp3a_done
